# attention: + saddr 32-bit load offsets, K/V LDS double buffer with one barrier per tile
# speedup vs baseline: 1.0101x; 1.0101x over previous
; __device__ __forceinline__ void attn_phase(LAS unsigned char* ldsb, bf16_t* P, const bf16_t* Kn, const bf16_t* KPE, const bf16_t* VT) {
;     ...
;             const int lane = tid & 63, w = __builtin_amdgcn_readfirstlane(tid >> 6), r = lane & 31, hh = lane >> 5;
;             const int qb = half ? 15 - jq : jq, q0 = qb * 256, nt = (q0 + 256) >> 6;
;             const int qabs = q0 + w * 32 + r;
;             bf16x8 qf[12];
;             { const bf16_t* qp = P + (rowbase + qabs) * LDP;
; #pragma unroll
;               for (int ks = 0; ks < 8; ++ks) qf[ks] = *(const bf16x8*)(qp + h * 128 + ks * 16 + hh * 8);
; #pragma unroll
;               for (int ks = 0; ks < 4; ++ks) qf[8 + ks] = *(const bf16x8*)(qp + 1024 + h * 64 + ks * 16 + hh * 8); }
;             f32x16 o[4];
; #pragma unroll
;             for (int d = 0; d < 4; ++d) for (int i = 0; i < 16; ++i) o[d][i] = 0.f;
;             float mrun = -INFINITY, lrun = 0.f;
;             u32x4 kst[3], vst[2];
.LBB0_1512:
	v_mov_b32_e32 v22, v232
	s_and_b64 s[6:7], s[76:77], exec
	v_readfirstlane_b32 s8, v22
	s_cselect_b32 s12, s33, s44
	s_ashr_i32 s6, s8, 1
	s_and_b32 s45, s6, 0xffffffe0
	v_and_b32_e32 v6, 31, v22
	s_add_i32 s45, s45, s12
	v_or_b32_e32 v228, s45, v6
	v_ashrrev_i32_e32 v229, 31, v228
	v_lshl_add_u64 v[2:3], s[60:61], 0, v[228:229]
	v_mad_u64_u32 v[226:227], s[6:7], v2, s5, v[224:225]
	v_bfe_u32 v12, v22, 5, 1
	v_mad_i32_i24 v227, v3, s5, v227
	v_lshl_add_u64 v[2:3], v[226:227], 0, s[16:17]
	v_lshlrev_b32_e32 v0, 4, v12
	v_lshl_add_u64 v[2:3], v[2:3], 0, v[0:1]
	global_load_dwordx4 v[220:223], v[2:3], off
	global_load_dwordx4 v[216:219], v[2:3], off offset:32
	global_load_dwordx4 v[212:215], v[2:3], off offset:64
	global_load_dwordx4 v[208:211], v[2:3], off offset:96
	global_load_dwordx4 v[204:207], v[2:3], off offset:128
	global_load_dwordx4 v[200:203], v[2:3], off offset:160
	global_load_dwordx4 v[196:199], v[2:3], off offset:192
	global_load_dwordx4 v[192:195], v[2:3], off offset:224
	v_lshl_add_u64 v[2:3], v[226:227], 0, s[72:73]
	v_lshl_add_u64 v[2:3], v[2:3], 0, v[0:1]
	global_load_dwordx4 v[188:191], v[2:3], off offset:2048
	global_load_dwordx4 v[184:187], v[2:3], off offset:2080
	global_load_dwordx4 v[180:183], v[2:3], off offset:2112
	global_load_dwordx4 v[176:179], v[2:3], off offset:2144
	v_mul_hi_i32 v0, v22, s20
	v_lshrrev_b32_e32 v2, 31, v0
	v_ashrrev_i32_e32 v0, 2, v0
	v_add_u32_e32 v2, v0, v2
	v_mul_lo_u32 v0, v2, 24
	v_sub_u32_e32 v23, v22, v0
	v_ashrrev_i32_e32 v3, 31, v2
	v_cmp_gt_i32_e64 s[6:7], 16, v23
	v_cmp_lt_i32_e32 vcc, 15, v23
	v_lshl_add_u64 v[10:11], s[60:61], 0, v[2:3]
	v_lshlrev_b32_e32 v4, 3, v23
	s_and_saveexec_b64 s[8:9], vcc
	s_xor_b64 s[8:9], exec, s[8:9]
	v_lshlrev_b64 v[8:9], 7, v[10:11]
	v_lshl_add_u64 v[8:9], s[14:15], 0, v[8:9]
	v_mov_b32_e32 v5, v1
	v_lshl_add_u64 v[8:9], v[4:5], 1, v[8:9]
	v_lshl_add_u64 v[8:9], v[8:9], 0, s[18:19]
	s_or_saveexec_b64 s[8:9], s[8:9]
	v_ashrrev_i32_e32 v7, 31, v4
	s_xor_b64 exec, exec, s[8:9]
	v_lshlrev_b64 v[8:9], 11, v[10:11]
	v_lshl_add_u64 v[8:9], s[64:65], 0, v[8:9]
	v_mov_b32_e32 v5, v7
	v_lshl_add_u64 v[8:9], v[4:5], 1, v[8:9]
	s_or_b64 exec, exec, s[8:9]
	global_load_dwordx4 v[112:115], v[8:9], off
	v_add_u32_e32 v24, 0x200, v22
	v_mul_hi_i32 v0, v24, s20
	v_lshrrev_b32_e32 v5, 31, v0
	v_ashrrev_i32_e32 v0, 2, v0
	v_add_u32_e32 v8, v0, v5
	v_mul_lo_u32 v0, v8, 24
	v_sub_u32_e32 v5, v24, v0
	v_ashrrev_i32_e32 v9, 31, v8
	v_cmp_gt_i32_e64 s[8:9], 16, v5
	v_cmp_lt_i32_e32 vcc, 15, v5
	v_lshl_add_u64 v[16:17], s[60:61], 0, v[8:9]
	v_lshlrev_b32_e32 v10, 3, v5
	s_and_saveexec_b64 s[10:11], vcc
	s_xor_b64 s[10:11], exec, s[10:11]
	v_lshlrev_b64 v[14:15], 7, v[16:17]
	v_lshl_add_u64 v[14:15], s[14:15], 0, v[14:15]
	v_mov_b32_e32 v11, v1
	v_lshl_add_u64 v[14:15], v[10:11], 1, v[14:15]
	v_lshl_add_u64 v[14:15], v[14:15], 0, s[18:19]
	s_or_saveexec_b64 s[10:11], s[10:11]
	v_ashrrev_i32_e32 v13, 31, v10
	s_xor_b64 exec, exec, s[10:11]
	v_lshlrev_b64 v[14:15], 11, v[16:17]
	v_lshl_add_u64 v[14:15], s[64:65], 0, v[14:15]
	v_mov_b32_e32 v11, v13
	v_lshl_add_u64 v[14:15], v[10:11], 1, v[14:15]
	s_or_b64 exec, exec, s[10:11]
	global_load_dwordx4 v[116:119], v[14:15], off
	v_add_u32_e32 v0, 0x400, v22
	v_mul_hi_i32 v11, v0, s20
	v_lshrrev_b32_e32 v14, 31, v11
	v_ashrrev_i32_e32 v11, 2, v11
	v_add_u32_e32 v14, v11, v14
	v_mul_lo_u32 v11, v14, 24
	v_sub_u32_e32 v11, v0, v11
	v_ashrrev_i32_e32 v15, 31, v14
	v_cmp_gt_i32_e64 s[10:11], 16, v11
	v_cmp_lt_i32_e32 vcc, 15, v11
	v_lshl_add_u64 v[20:21], s[60:61], 0, v[14:15]
	v_lshlrev_b32_e32 v0, 3, v11
	s_and_saveexec_b64 s[34:35], vcc
	s_xor_b64 s[74:75], exec, s[34:35]
	v_lshlrev_b64 v[16:17], 7, v[20:21]
	v_lshl_add_u64 v[16:17], s[14:15], 0, v[16:17]
	v_lshl_add_u64 v[16:17], v[0:1], 1, v[16:17]
	v_lshl_add_u64 v[18:19], v[16:17], 0, s[18:19]
	s_or_saveexec_b64 s[74:75], s[74:75]
	v_mov_b64_e32 v[16:17], v[0:1]
	s_xor_b64 exec, exec, s[74:75]
	v_lshlrev_b64 v[16:17], 11, v[20:21]
	v_lshl_add_u64 v[18:19], s[64:65], 0, v[16:17]
	v_ashrrev_i32_e32 v17, 31, v0
	v_mov_b32_e32 v16, v0
	v_lshl_add_u64 v[18:19], v[16:17], 1, v[18:19]
	s_or_b64 exec, exec, s[74:75]
	global_load_dwordx4 v[120:123], v[18:19], off
	v_lshlrev_b32_e32 v18, 4, v22
	v_ashrrev_i32_e32 v26, 3, v22
	v_and_b32_e32 v18, 0x70, v18
	v_mov_b32_e32 v19, v1
	v_ashrrev_i32_e32 v27, 31, v26
	v_ashrrev_i32_e32 v24, 3, v24
	v_lshl_add_u64 v[20:21], s[62:63], 0, v[18:19]
	v_lshlrev_b64 v[28:29], 13, v[26:27]
	v_ashrrev_i32_e32 v25, 31, v24
	v_lshl_add_u64 v[30:31], v[20:21], 0, v[28:29]
	v_lshlrev_b64 v[32:33], 13, v[24:25]
	v_lshl_add_u64 v[20:21], v[20:21], 0, v[32:33]
	global_load_dwordx4 v[128:131], v[30:31], off
; #define LAS __attribute__((address_space(3)))
; __device__ __forceinline__ void attn_phase(LAS unsigned char* ldsb, bf16_t* P, const bf16_t* Kn, const bf16_t* KPE, const bf16_t* VT) {
;     ...
;             f32x16 o[4];
; #pragma unroll
;             for (int d = 0; d < 4; ++d) for (int i = 0; i < 16; ++i) o[d][i] = 0.f;
;             float mrun = -INFINITY, lrun = 0.f;
;             u32x4 kst[3], vst[2];
;     ...
;             ATT_LOAD(0);
;             for (int kt = 0; kt < nt; ++kt) {
;                 __syncthreads();
; #pragma unroll
;                 for (int i = 0; i < 3; ++i) { const int id = tid + 512 * i, row = id / 24, ch = id % 24; *(LAS u32x4*)(sK + row * 200 + ch * 8) = kst[i]; }
; #pragma unroll
;                 for (int i = 0; i < 2; ++i) { const int id = tid + 512 * i, d = id >> 3, ch = id & 7;
;                     *(LAS u32x2*)(sVt + d * 68 + ch * 8) = (u32x2){vst[i].x, vst[i].y}; *(LAS u32x2*)(sVt + d * 68 + ch * 8 + 4) = (u32x2){vst[i].z, vst[i].w}; }
;                 __syncthreads();
;                 if (kt + 1 < nt) ATT_LOAD(kt + 1);
	global_load_dwordx4 v[124:127], v[20:21], off
	v_lshlrev_b32_e32 v34, 3, v12
	v_add_u32_e32 v25, 0, v18
	v_mad_u32_u24 v18, v6, s21, 0
	v_mul_i32_i24_e32 v6, 0xfffffef8, v6
	v_and_b32_e32 v20, 7, v22
	v_lshl_add_u32 v241, v12, 4, v18
	v_add3_u32 v6, v18, v6, v34
	v_lshl_add_u64 v[18:19], s[66:67], 0, v[28:29]
	v_lshlrev_b32_e32 v20, 4, v20
	v_mov_b32_e32 v21, v1
	v_add_u32_e32 v239, 0x6400, v6
	v_add_u32_e32 v238, 0x7500, v6
	v_add_u32_e32 v237, 0x8600, v6
	v_add_u32_e32 v235, 0x9700, v6
	v_mul_lo_u32 v6, v2, s21
	v_lshl_add_u64 v[132:133], v[18:19], 0, v[20:21]
	v_lshl_add_u64 v[18:19], s[66:67], 0, v[32:33]
	v_add_u32_e32 v27, 0, v6
	v_mul_lo_u32 v6, v8, s21
	v_lshl_add_u64 v[134:135], v[18:19], 0, v[20:21]
	v_lshlrev_b64 v[18:19], 7, v[2:3]
	v_lshlrev_b64 v[2:3], 11, v[2:3]
	v_add_u32_e32 v30, 0, v6
	v_mov_b32_e32 v6, v4
	v_lshl_add_u64 v[2:3], s[70:71], 0, v[2:3]
	v_lshl_add_u64 v[138:139], v[6:7], 1, v[2:3]
	v_lshlrev_b64 v[2:3], 7, v[8:9]
	v_lshlrev_b32_e32 v35, 4, v11
	v_mov_b32_e32 v11, v1
	v_lshl_add_u64 v[2:3], s[68:69], 0, v[2:3]
	v_lshl_add_u64 v[140:141], v[10:11], 1, v[2:3]
	v_lshlrev_b64 v[2:3], 11, v[8:9]
	v_lshlrev_b32_e32 v229, 2, v12
	v_mov_b32_e32 v12, v10
	v_lshl_add_u64 v[2:3], s[70:71], 0, v[2:3]
	v_lshl_add_u64 v[142:143], v[12:13], 1, v[2:3]
	v_lshlrev_b64 v[2:3], 7, v[14:15]
	v_lshl_add_u64 v[2:3], s[68:69], 0, v[2:3]
	v_lshlrev_b32_e32 v31, 4, v5
	v_mul_lo_u32 v5, v14, s21
	v_lshl_add_u64 v[144:145], v[0:1], 1, v[2:3]
	v_lshlrev_b64 v[2:3], 11, v[14:15]
	s_addk_i32 s12, 0x100
	v_lshlrev_b32_e32 v23, 4, v23
	v_add_u32_e32 v34, 0, v5
	v_mul_lo_u32 v26, v26, s30
	v_mul_lo_u32 v24, v24, s30
	v_mov_b32_e32 v5, v1
	v_lshl_add_u64 v[18:19], s[68:69], 0, v[18:19]
	v_lshl_add_u64 v[2:3], s[70:71], 0, v[2:3]
	v_mov_b32_e32 v14, v1
	v_mov_b32_e32 v15, v1
	s_lshr_b32 s12, s12, 6
	v_lshl_add_u64 v[136:137], v[4:5], 1, v[18:19]
	v_lshl_add_u64 v[146:147], v[16:17], 1, v[2:3]
	v_mov_b32_e32 v0, v1
	v_mov_b32_e32 v2, v1
	v_mov_b32_e32 v3, v1
	v_mov_b32_e32 v4, v1
	v_mov_b32_e32 v6, v1
	v_mov_b32_e32 v7, v1
	v_mov_b32_e32 v8, v1
	v_mov_b32_e32 v9, v1
	v_mov_b32_e32 v10, v1
	v_mov_b32_e32 v12, v1
	v_mov_b32_e32 v13, v1
	v_add_u32_e32 v148, v27, v23
	v_add_u32_e32 v149, v30, v31
	v_add_u32_e32 v150, v34, v35
	v_add3_u32 v151, v25, v26, s29
	v_add3_u32 v152, v25, v24, s29
	v_mov_b64_e32 v[30:31], v[14:15]
	v_mov_b64_e32 v[46:47], v[14:15]
	v_mov_b64_e32 v[62:63], v[14:15]
	v_mov_b64_e32 v[78:79], v[14:15]
	s_xor_b64 s[74:75], s[76:77], -1
	s_or_b32 s76, s45, 31
	s_add_i32 s77, s12, -1
	v_mov_b32_e32 v240, 0xff800000
	v_mov_b32_e32 v236, 0
	s_mov_b32 s78, 63
	v_mov_b64_e32 v[28:29], v[12:13]
	v_mov_b64_e32 v[26:27], v[10:11]
	v_mov_b64_e32 v[24:25], v[8:9]
	v_mov_b64_e32 v[22:23], v[6:7]
	v_mov_b64_e32 v[20:21], v[4:5]
	v_mov_b64_e32 v[18:19], v[2:3]
	v_mov_b64_e32 v[16:17], v[0:1]
	v_mov_b64_e32 v[44:45], v[12:13]
	v_mov_b64_e32 v[42:43], v[10:11]
	v_mov_b64_e32 v[40:41], v[8:9]
	v_mov_b64_e32 v[38:39], v[6:7]
	v_mov_b64_e32 v[36:37], v[4:5]
	v_mov_b64_e32 v[34:35], v[2:3]
	v_mov_b64_e32 v[32:33], v[0:1]
	v_mov_b64_e32 v[60:61], v[12:13]
	v_mov_b64_e32 v[58:59], v[10:11]
	v_mov_b64_e32 v[56:57], v[8:9]
	v_mov_b64_e32 v[54:55], v[6:7]
	v_mov_b64_e32 v[52:53], v[4:5]
	v_mov_b64_e32 v[50:51], v[2:3]
	v_mov_b64_e32 v[48:49], v[0:1]
	v_mov_b64_e32 v[76:77], v[12:13]
	v_mov_b64_e32 v[74:75], v[10:11]
	v_mov_b64_e32 v[72:73], v[8:9]
	v_mov_b64_e32 v[70:71], v[6:7]
	v_mov_b64_e32 v[68:69], v[4:5]
	v_mov_b64_e32 v[66:67], v[2:3]
	v_mov_b64_e32 v[64:65], v[0:1]
	s_barrier
	s_waitcnt vmcnt(4)
	ds_write_b128 v148, v[112:115]
	s_waitcnt vmcnt(3)
	ds_write_b128 v149, v[116:119]
	s_waitcnt vmcnt(2)
	ds_write_b128 v150, v[120:123]
	s_waitcnt vmcnt(1)
	ds_write2_b64 v151, v[128:129], v[130:131] offset1:1
	s_waitcnt vmcnt(0)
	ds_write2_b64 v152, v[124:125], v[126:127] offset1:1
	v_cndmask_b32_e64 v2, v136, v138, s[6:7]
	v_cndmask_b32_e64 v3, v140, v142, s[8:9]
	v_cndmask_b32_e64 v4, v144, v146, s[10:11]
	s_waitcnt lgkmcnt(0)
	s_barrier
	global_load_dwordx4 v[112:115], v2, s[26:27]
	global_load_dwordx4 v[116:119], v3, s[26:27]
	global_load_dwordx4 v[120:123], v4, s[26:27]
	global_load_dwordx4 v[128:131], v132, s[26:27]
	global_load_dwordx4 v[124:127], v134, s[26:27]
	v_add_u32_e32 v132, 0x80, v132
	v_add_u32_e32 v134, 0x80, v134
	v_add_u32_e32 v136, 0x2000, v136
	v_add_u32_e32 v138, 0x20000, v138
	v_add_u32_e32 v140, 0x2000, v140
	v_add_u32_e32 v142, 0x20000, v142
	v_add_u32_e32 v144, 0x2000, v144
	v_add_u32_e32 v146, 0x20000, v146
	v_xor_b32_e32 v148, 0x10000, v148
	v_xor_b32_e32 v149, 0x10000, v149
	v_xor_b32_e32 v150, 0x10000, v150
	v_xor_b32_e32 v151, 0x10000, v151
	v_xor_b32_e32 v152, 0x10000, v152
	s_branch .LBB0_1527

; #define LAS __attribute__((address_space(3)))
; __device__ __forceinline__ void attn_phase(LAS unsigned char* ldsb, bf16_t* P, const bf16_t* Kn, const bf16_t* KPE, const bf16_t* VT) {
;     ...
;             for (int kt = 0; kt < nt; ++kt) {
;                 __syncthreads();
; #pragma unroll
;                 for (int i = 0; i < 3; ++i) { const int id = tid + 512 * i, row = id / 24, ch = id % 24; *(LAS u32x4*)(sK + row * 200 + ch * 8) = kst[i]; }
; #pragma unroll
;                 for (int i = 0; i < 2; ++i) { const int id = tid + 512 * i, d = id >> 3, ch = id & 7;
;                     *(LAS u32x2*)(sVt + d * 68 + ch * 8) = (u32x2){vst[i].x, vst[i].y}; *(LAS u32x2*)(sVt + d * 68 + ch * 8 + 4) = (u32x2){vst[i].z, vst[i].w}; }
;                 __syncthreads();
;                 if (kt + 1 < nt) ATT_LOAD(kt + 1);
.LBB0_1526:
	s_add_i32 s77, s77, -1
	s_add_i32 s78, s78, 64
	v_xor_b32_e32 v241, 0x10000, v241
	v_xor_b32_e32 v235, 0x10000, v235
	v_xor_b32_e32 v237, 0x10000, v237
	v_xor_b32_e32 v238, 0x10000, v238
	v_xor_b32_e32 v239, 0x10000, v239
	s_waitcnt lgkmcnt(0)
	s_barrier
	s_cmp_eq_u32 s77, 0
	s_cbranch_scc1 .LBB0_1532
	v_xor_b32_e32 v148, 0x10000, v148
	v_xor_b32_e32 v149, 0x10000, v149
	v_xor_b32_e32 v150, 0x10000, v150
	v_xor_b32_e32 v151, 0x10000, v151
	v_xor_b32_e32 v152, 0x10000, v152
.LBB0_1527:
	s_cmp_lt_u32 s77, 2
	s_cbranch_scc1 .Lattn_nopre
	s_waitcnt vmcnt(4)
	ds_write_b128 v148, v[112:115]
	s_waitcnt vmcnt(3)
	ds_write_b128 v149, v[116:119]
	s_waitcnt vmcnt(2)
	ds_write_b128 v150, v[120:123]
	s_waitcnt vmcnt(1)
	ds_write2_b64 v151, v[128:129], v[130:131] offset1:1
	s_waitcnt vmcnt(0)
	ds_write2_b64 v152, v[124:125], v[126:127] offset1:1
	v_cndmask_b32_e64 v2, v136, v138, s[6:7]
	v_cndmask_b32_e64 v3, v140, v142, s[8:9]
	v_cndmask_b32_e64 v4, v144, v146, s[10:11]
	s_waitcnt lgkmcnt(0)
	global_load_dwordx4 v[112:115], v2, s[26:27]
	global_load_dwordx4 v[116:119], v3, s[26:27]
	global_load_dwordx4 v[120:123], v4, s[26:27]
	global_load_dwordx4 v[128:131], v132, s[26:27]
	global_load_dwordx4 v[124:127], v134, s[26:27]
	v_add_u32_e32 v132, 0x80, v132
	v_add_u32_e32 v134, 0x80, v134
	v_add_u32_e32 v136, 0x2000, v136
	v_add_u32_e32 v138, 0x20000, v138
	v_add_u32_e32 v140, 0x2000, v140
	v_add_u32_e32 v142, 0x20000, v142
	v_add_u32_e32 v144, 0x2000, v144
	v_add_u32_e32 v146, 0x20000, v146
; DI int crow(int reg, int hh) { return (reg & 3) + 8 * (reg >> 2) + 4 * hh; }
; #define ATT_RD(dst, off) asm volatile("ds_read_b128 %0, %1 offset:" #off : "=&v"(dst) : "v"(kaddr) : "memory")
; __device__ __forceinline__ void attn_phase(LAS unsigned char* ldsb, bf16_t* P, const bf16_t* Kn, const bf16_t* KPE, const bf16_t* VT) {
;     ...
;                 const int k0 = kt * 64;
;                 if (k0 <= q0 + w * 32 + 31) {
;                     f32x16 st[2];
; #pragma unroll
;                     for (int kb = 0; kb < 2; ++kb) for (int i = 0; i < 16; ++i) st[kb][i] = 0.f;
;                     {
;                         const unsigned kaddr = (unsigned)(size_t)(sK + r * 200 + hh * 8);
;                         bf16x8 ka0, ka1, kb0, kb1;
;     ...
;                         ATT_RD(ka0, 0);   ATT_RD(ka1, 12800);
;                         ATT_RD(kb0, 32);  ATT_RD(kb1, 12832);  ATT_WT(2, ka0, ka1); ATT_MM(ka0, ka1, 0);
;                         ATT_RD(ka0, 64);  ATT_RD(ka1, 12864);  ATT_WT(2, kb0, kb1); ATT_MM(kb0, kb1, 1);
;                         ATT_RD(kb0, 96);  ATT_RD(kb1, 12896);  ATT_WT(2, ka0, ka1); ATT_MM(ka0, ka1, 2);
;                         ATT_RD(ka0, 128); ATT_RD(ka1, 12928);  ATT_WT(2, kb0, kb1); ATT_MM(kb0, kb1, 3);
;                         ATT_RD(kb0, 160); ATT_RD(kb1, 12960);  ATT_WT(2, ka0, ka1); ATT_MM(ka0, ka1, 4);
;                         ATT_RD(ka0, 192); ATT_RD(ka1, 12992);  ATT_WT(2, kb0, kb1); ATT_MM(kb0, kb1, 5);
;                         ATT_RD(kb0, 224); ATT_RD(kb1, 13024);  ATT_WT(2, ka0, ka1); ATT_MM(ka0, ka1, 6);
;                         ATT_RD(ka0, 256); ATT_RD(ka1, 13056);  ATT_WT(2, kb0, kb1); ATT_MM(kb0, kb1, 7);
;                         ATT_RD(kb0, 288); ATT_RD(kb1, 13088);  ATT_WT(2, ka0, ka1); ATT_MM(ka0, ka1, 8);
;                         ATT_RD(ka0, 320); ATT_RD(ka1, 13120);  ATT_WT(2, kb0, kb1); ATT_MM(kb0, kb1, 9);
;                         ATT_RD(kb0, 352); ATT_RD(kb1, 13152);  ATT_WT(2, ka0, ka1); ATT_MM(ka0, ka1, 10);
;                         ATT_WT(0, kb0, kb1); ATT_MM(kb0, kb1, 11);
;     ...
;                     }
;                     if (k0 + 63 > q0 + w * 32) {
; #pragma unroll
;                         for (int kb = 0; kb < 2; ++kb)
; #pragma unroll
;                             for (int i = 0; i < 16; ++i) { const int key = k0 + kb * 32 + crow(i, hh); if (key > qabs) st[kb][i] = -INFINITY; }
;                     }
.Lattn_nopre:
	s_sub_i32 s12, s78, 63
	s_cmp_gt_i32 s12, s76
	s_cbranch_scc1 .LBB0_1526
	ds_read_b128 v[2:5], v241 offset:0
	ds_read_b128 v[6:9], v241 offset:12800
	ds_read_b128 v[10:13], v241 offset:32
	ds_read_b128 v[154:157], v241 offset:12832
	ds_read_b128 v[158:161], v241 offset:64
	ds_read_b128 v[162:165], v241 offset:12864
	ds_read_b128 v[166:169], v241 offset:96
	ds_read_b128 v[170:173], v241 offset:12896
	s_cmp_le_i32 s78, s45
	s_waitcnt lgkmcnt(6)
	v_mfma_f32_32x32x16_bf16 v[96:111], v[2:5], v[220:223], 0
	ds_read_b128 v[2:5], v241 offset:128
	v_mfma_f32_32x32x16_bf16 v[80:95], v[6:9], v[220:223], 0
	ds_read_b128 v[6:9], v241 offset:12928
	s_waitcnt lgkmcnt(6)
	v_mfma_f32_32x32x16_bf16 v[96:111], v[10:13], v[216:219], v[96:111]
	ds_read_b128 v[10:13], v241 offset:160
	v_mfma_f32_32x32x16_bf16 v[80:95], v[154:157], v[216:219], v[80:95]
	ds_read_b128 v[154:157], v241 offset:12960
	s_waitcnt lgkmcnt(6)
	v_mfma_f32_32x32x16_bf16 v[96:111], v[158:161], v[212:215], v[96:111]
	ds_read_b128 v[158:161], v241 offset:192
	v_mfma_f32_32x32x16_bf16 v[80:95], v[162:165], v[212:215], v[80:95]
	ds_read_b128 v[162:165], v241 offset:12992
	s_waitcnt lgkmcnt(6)
	v_mfma_f32_32x32x16_bf16 v[96:111], v[166:169], v[208:211], v[96:111]
	ds_read_b128 v[166:169], v241 offset:224
	v_mfma_f32_32x32x16_bf16 v[80:95], v[170:173], v[208:211], v[80:95]
	ds_read_b128 v[170:173], v241 offset:13024
	s_waitcnt lgkmcnt(6)
	v_mfma_f32_32x32x16_bf16 v[96:111], v[2:5], v[204:207], v[96:111]
	ds_read_b128 v[2:5], v241 offset:256
	v_mfma_f32_32x32x16_bf16 v[80:95], v[6:9], v[204:207], v[80:95]
	ds_read_b128 v[6:9], v241 offset:13056
	s_waitcnt lgkmcnt(6)
	v_mfma_f32_32x32x16_bf16 v[96:111], v[10:13], v[200:203], v[96:111]
	ds_read_b128 v[10:13], v241 offset:288
	v_mfma_f32_32x32x16_bf16 v[80:95], v[154:157], v[200:203], v[80:95]
	ds_read_b128 v[154:157], v241 offset:13088
	s_waitcnt lgkmcnt(6)
	v_mfma_f32_32x32x16_bf16 v[96:111], v[158:161], v[196:199], v[96:111]
	ds_read_b128 v[158:161], v241 offset:320
	v_mfma_f32_32x32x16_bf16 v[80:95], v[162:165], v[196:199], v[80:95]
	ds_read_b128 v[162:165], v241 offset:13120
	s_waitcnt lgkmcnt(6)
	v_mfma_f32_32x32x16_bf16 v[96:111], v[166:169], v[192:195], v[96:111]
	ds_read_b128 v[166:169], v241 offset:352
	v_mfma_f32_32x32x16_bf16 v[80:95], v[170:173], v[192:195], v[80:95]
	ds_read_b128 v[170:173], v241 offset:13152
	s_waitcnt lgkmcnt(6)
	v_mfma_f32_32x32x16_bf16 v[96:111], v[2:5], v[188:191], v[96:111]
	v_mfma_f32_32x32x16_bf16 v[80:95], v[6:9], v[188:191], v[80:95]
	s_waitcnt lgkmcnt(4)
	v_mfma_f32_32x32x16_bf16 v[96:111], v[10:13], v[184:187], v[96:111]
	v_mfma_f32_32x32x16_bf16 v[80:95], v[154:157], v[184:187], v[80:95]
	s_waitcnt lgkmcnt(2)
	v_mfma_f32_32x32x16_bf16 v[96:111], v[158:161], v[180:183], v[96:111]
	v_mfma_f32_32x32x16_bf16 v[80:95], v[162:165], v[180:183], v[80:95]
	s_waitcnt lgkmcnt(0)
	v_mfma_f32_32x32x16_bf16 v[96:111], v[166:169], v[176:179], v[96:111]
	v_mfma_f32_32x32x16_bf16 v[80:95], v[170:173], v[176:179], v[80:95]
	s_cbranch_scc1 .LBB0_1530
	v_add_u32_e32 v0, s78, v229
	v_subrev_u32_e32 v2, 63, v0
	v_cmp_gt_i32_e32 vcc, v2, v228
	s_nop 6
	v_cndmask_b32_e32 v3, v96, v233, vcc
	v_cmp_lt_i32_e32 vcc, v2, v228
	v_subrev_u32_e32 v2, 61, v0
	s_nop 0
	v_cndmask_b32_e32 v96, v3, v96, vcc
	v_cndmask_b32_e32 v97, v233, v97, vcc
	v_cmp_le_i32_e32 vcc, v2, v228
	v_subrev_u32_e32 v2, 60, v0
	s_nop 0
	v_cndmask_b32_e32 v98, v233, v98, vcc
	v_cmp_le_i32_e32 vcc, v2, v228
	v_subrev_u32_e32 v2, 55, v0
	s_nop 0
	v_cndmask_b32_e32 v99, v233, v99, vcc
	v_cmp_le_i32_e32 vcc, v2, v228
	v_subrev_u32_e32 v2, 54, v0
	s_nop 0
	v_cndmask_b32_e32 v100, v233, v100, vcc
	v_cmp_le_i32_e32 vcc, v2, v228
	v_subrev_u32_e32 v2, 53, v0
	s_nop 0
	v_cndmask_b32_e32 v101, v233, v101, vcc
	v_cmp_le_i32_e32 vcc, v2, v228
	v_subrev_u32_e32 v2, 52, v0
	s_nop 0
	v_cndmask_b32_e32 v102, v233, v102, vcc
	v_cmp_le_i32_e32 vcc, v2, v228
	v_subrev_u32_e32 v2, 47, v0
	s_nop 0
	v_cndmask_b32_e32 v103, v233, v103, vcc
	v_cmp_le_i32_e32 vcc, v2, v228
	v_subrev_u32_e32 v2, 46, v0
	s_nop 0
	v_cndmask_b32_e32 v104, v233, v104, vcc
	v_cmp_le_i32_e32 vcc, v2, v228
	v_subrev_u32_e32 v2, 45, v0
	s_nop 0
	v_cndmask_b32_e32 v105, v233, v105, vcc
	v_cmp_le_i32_e32 vcc, v2, v228
	v_subrev_u32_e32 v2, 44, v0
	s_nop 0
	v_cndmask_b32_e32 v106, v233, v106, vcc
	v_cmp_le_i32_e32 vcc, v2, v228
	v_subrev_u32_e32 v2, 39, v0
	s_nop 0
	v_cndmask_b32_e32 v107, v233, v107, vcc
	v_cmp_le_i32_e32 vcc, v2, v228
	v_subrev_u32_e32 v2, 38, v0
	s_nop 0
	v_cndmask_b32_e32 v108, v233, v108, vcc
	v_cmp_le_i32_e32 vcc, v2, v228
	v_subrev_u32_e32 v2, 37, v0
	s_nop 0
	v_cndmask_b32_e32 v109, v233, v109, vcc
	v_cmp_le_i32_e32 vcc, v2, v228
	v_subrev_u32_e32 v2, 36, v0
	s_nop 0
	v_cndmask_b32_e32 v110, v233, v110, vcc
	v_cmp_le_i32_e32 vcc, v2, v228
	v_subrev_u32_e32 v2, 31, v0
	s_nop 0
	v_cndmask_b32_e32 v111, v233, v111, vcc
	v_cmp_le_i32_e32 vcc, v2, v228
	v_subrev_u32_e32 v2, 30, v0
	s_nop 0
	v_cndmask_b32_e32 v80, v233, v80, vcc
	v_cmp_le_i32_e32 vcc, v2, v228
	v_subrev_u32_e32 v2, 29, v0
	s_nop 0
	v_cndmask_b32_e32 v81, v233, v81, vcc
	v_cmp_le_i32_e32 vcc, v2, v228
	v_subrev_u32_e32 v2, 28, v0
	s_nop 0
	v_cndmask_b32_e32 v82, v233, v82, vcc
	v_cmp_le_i32_e32 vcc, v2, v228
	v_subrev_u32_e32 v2, 23, v0
	s_nop 0
	v_cndmask_b32_e32 v83, v233, v83, vcc
	v_cmp_le_i32_e32 vcc, v2, v228
	v_subrev_u32_e32 v2, 22, v0
	s_nop 0
	v_cndmask_b32_e32 v84, v233, v84, vcc
	v_cmp_le_i32_e32 vcc, v2, v228
	v_subrev_u32_e32 v2, 21, v0
	s_nop 0
	v_cndmask_b32_e32 v85, v233, v85, vcc
	v_cmp_le_i32_e32 vcc, v2, v228
	v_subrev_u32_e32 v2, 20, v0
	s_nop 0
	v_cndmask_b32_e32 v86, v233, v86, vcc
	v_cmp_le_i32_e32 vcc, v2, v228
	v_add_u32_e32 v2, -15, v0
	s_nop 0
	v_cndmask_b32_e32 v87, v233, v87, vcc
	v_cmp_le_i32_e32 vcc, v2, v228
	v_add_u32_e32 v2, -14, v0
	s_nop 0
	v_cndmask_b32_e32 v88, v233, v88, vcc
	v_cmp_le_i32_e32 vcc, v2, v228
	v_add_u32_e32 v2, -13, v0
	s_nop 0
	v_cndmask_b32_e32 v89, v233, v89, vcc
	v_cmp_le_i32_e32 vcc, v2, v228
	v_add_u32_e32 v2, -12, v0
	s_nop 0
	v_cndmask_b32_e32 v90, v233, v90, vcc
	v_cmp_le_i32_e32 vcc, v2, v228
	v_add_u32_e32 v2, -7, v0
	s_nop 0
	v_cndmask_b32_e32 v91, v233, v91, vcc
	v_cmp_le_i32_e32 vcc, v2, v228
	v_add_u32_e32 v2, -6, v0
	s_nop 0
	v_cndmask_b32_e32 v92, v233, v92, vcc
	v_cmp_le_i32_e32 vcc, v2, v228
	v_add_u32_e32 v2, -5, v0
	v_add_u32_e32 v0, -4, v0
	v_cndmask_b32_e32 v93, v233, v93, vcc
	v_cmp_le_i32_e32 vcc, v2, v228
	s_nop 1
	v_cndmask_b32_e32 v94, v233, v94, vcc
	v_cmp_le_i32_e32 vcc, v0, v228
	s_nop 1
	v_cndmask_b32_e32 v95, v233, v95, vcc
